# remaining four GEMM phase prologues (P4, P7, P8b, P11) also issue all 14 LDS-DMA pieces before the first wait
# baseline (speedup 1.0000x reference)
; #define PG8_STAGE(bufoff, gbase, voff) do { _Pragma("unroll") for (int _i = 0; _i < 2; ++_i) \
;         __builtin_amdgcn_global_load_lds((const unsigned*)((const char*)(gbase) + (voff)[_i]), (PG8_LAS unsigned*)(lds + (bufoff) + ldsw + _i * 8192), 16, 0, 0); } while (0)
; #define PG8_WAIT_V(n) asm volatile("s_waitcnt vmcnt(" #n ")" ::: "memory")
; #define PG8_BAR __builtin_amdgcn_s_barrier()
; template <class Epi, class Sched, bool ALIGN_EPI = false, bool SP2 = false>
; __device__ __forceinline__ void gemm_phase(PG8_LAS unsigned char* lds, const Gemm g, const Sched& S, const Epi& E) {
;     const int tid = threadIdx.x, wid = __builtin_amdgcn_readfirstlane(tid >> 6), lane = tid & 63, wr = wid >> 2, wc = wid & 3, fr = lane & 15, fq = lane >> 4;
;     const int K = g.K, nt = K / BK;
;     unsigned voffA[2], voffB[2];
; #pragma unroll
;     for (int i = 0; i < 2; ++i) { int R, C; stage_rc(tid * 16 + i * 8192, R, C); const int Rb = Epi::PERM ? ((R & ~31) + perm32(R & 31)) : R;
;         voffA[i] = (unsigned)(R * g.lda + C) * 2u; voffB[i] = (unsigned)(Rb * g.ldb + C) * 2u; }
;     const size_t kstep = (size_t)(BK * 2);
;     const size_t hstepA = (size_t)HALF * g.lda * 2, hstepB = (size_t)HALF * g.ldb * 2;
;     const size_t tstepA = 2 * hstepA, tstepB = 2 * hstepB;
;     const unsigned ldsw = (unsigned)wid * 1024u;
;     const int aoff = lds_byte(wr * 64 + fr, fq * 8), boff = lds_byte(wc * 32 + fr, fq * 8);
;     ...
;         PG8_STAGE(PG8_SB(0, 0), cB, voffB); PG8_STAGE(PG8_SB(0, 1), cB + hstepB, voffB); PG8_STAGE(PG8_SA(0, 0), cA, voffA); PG8_STAGE(PG8_SA(0, 1), cA + hstepA, voffA);
;         if (wr == 1) PG8_BAR;
;         PG8_WAIT_V(2); PG8_BAR;
;         PG8_STAGE(PG8_SB(1, 0), cB + kstep, voffB); PG8_STAGE(PG8_SA(1, 0), cA + kstep, voffA); PG8_STAGE(PG8_SB(1, 1), cB + hstepB + kstep, voffB);
;         PG8_WAIT_V(6); PG8_BAR;
.LBB0_840:
	v_readlane_b32 s16, v240, 3
	v_readlane_b32 s17, v240, 4
	s_add_u32 s10, s16, 0x15802800
	s_addc_u32 s11, s17, 0
	s_lshl_b32 s5, s5, 5
	s_mov_b64 s[16:17], 0x80
	s_and_b32 s5, s5, 0x60
	s_add_i32 m0, s46, 0x18000
	v_lshl_add_u64 v[6:7], v[6:7], 0, s[16:17]
	v_readlane_b32 s18, v240, 5
	s_lshl_b32 s20, s4, 13
	s_lshl_b32 s21, s5, 7
	global_load_lds_dwordx4 v[6:7], off
	v_lshl_add_u64 v[4:5], v[4:5], 0, s[16:17]
	s_add_i32 m0, s46, 0x1a000
	s_waitcnt lgkmcnt(0)
	s_add_i32 s52, s46, 0x8000
	s_add_i32 s53, s46, 0xa000
	v_readlane_b32 s19, v240, 6
	global_load_lds_dwordx4 v[4:5], off
	v_lshl_add_u64 v[0:1], v[0:1], 0, s[16:17]
	s_mov_b32 m0, s52
	s_add_u32 s18, s42, 0x40080
	global_load_lds_dwordx4 v[0:1], off
	v_lshl_add_u64 v[0:1], v[2:3], 0, s[16:17]
	s_mov_b32 m0, s53
	s_addc_u32 s19, s43, 0
	global_load_lds_dwordx4 v[0:1], off
	s_add_i32 m0, s46, 0x1c000
	v_lshl_add_u64 v[0:1], s[18:19], 0, v[132:133]
	global_load_lds_dwordx4 v[0:1], off
	v_lshl_add_u64 v[0:1], s[18:19], 0, v[128:129]
	s_add_i32 m0, s46, 0x1e000
	s_sext_i32_i8 s29, s0
	global_load_lds_dwordx4 v[0:1], off
	s_waitcnt vmcnt(8)
	s_barrier
	v_and_b32_e32 v0, 15, v162
	v_lshlrev_b32_e32 v1, 1, v8
	v_lshlrev_b32_e32 v2, 2, v162
	v_lshlrev_b32_e32 v3, 6, v162
	s_movk_i32 s0, 0x3c0
	v_lshl_or_b32 v152, s4, 6, v0
	v_lshl_or_b32 v0, v0, 6, v1
	v_and_b32_e32 v2, 32, v2
	v_and_or_b32 v1, v3, s0, v1
	s_waitcnt vmcnt(6)
	s_cmpk_lt_u32 s1, 0x100
	v_bitop3_b32 v0, v0, s20, v2 bitop3:0xde
	v_bitop3_b32 v153, s21, v1, v2 bitop3:0xf6
	s_cselect_b64 s[18:19], -1, 0
	s_add_i32 s54, 0, 0x10000
	s_add_i32 s55, 0, 0x14000
	v_or_b32_e32 v154, s5, v8
	v_add3_u32 v136, v12, v9, v10
	v_mov_b32_e32 v137, v133
	v_add3_u32 v138, v11, v9, v10
	v_mov_b32_e32 v139, v133
	v_mov_b64_e32 v[140:141], 0x420
	v_mov_b64_e32 v[142:143], 0x41f
	v_add_u32_e32 v155, s54, v153
	v_add_u32_e32 v156, s55, v153
	v_add_u32_e32 v157, 0, v0
	s_mov_b32 s56, 0xc1f00000
	v_mov_b32_e32 v158, 0x41f00000
	s_barrier
	s_branch .LBB0_843

; #define PG8_STAGE(bufoff, gbase, voff) do { _Pragma("unroll") for (int _i = 0; _i < 2; ++_i) \
;         __builtin_amdgcn_global_load_lds((const unsigned*)((const char*)(gbase) + (voff)[_i]), (PG8_LAS unsigned*)(lds + (bufoff) + ldsw + _i * 8192), 16, 0, 0); } while (0)
; #define PG8_WAIT_V(n) asm volatile("s_waitcnt vmcnt(" #n ")" ::: "memory")
; #define PG8_BAR __builtin_amdgcn_s_barrier()
; template <class Epi, class Sched, bool ALIGN_EPI = false, bool SP2 = false>
; __device__ __forceinline__ void gemm_phase(PG8_LAS unsigned char* lds, const Gemm g, const Sched& S, const Epi& E) {
;     const int tid = threadIdx.x, wid = __builtin_amdgcn_readfirstlane(tid >> 6), lane = tid & 63, wr = wid >> 2, wc = wid & 3, fr = lane & 15, fq = lane >> 4;
;     const int K = g.K, nt = K / BK;
;     unsigned voffA[2], voffB[2];
; #pragma unroll
;     for (int i = 0; i < 2; ++i) { int R, C; stage_rc(tid * 16 + i * 8192, R, C); const int Rb = Epi::PERM ? ((R & ~31) + perm32(R & 31)) : R;
;         voffA[i] = (unsigned)(R * g.lda + C) * 2u; voffB[i] = (unsigned)(Rb * g.ldb + C) * 2u; }
;     const size_t kstep = (size_t)(BK * 2);
;     const size_t hstepA = (size_t)HALF * g.lda * 2, hstepB = (size_t)HALF * g.ldb * 2;
;     const size_t tstepA = 2 * hstepA, tstepB = 2 * hstepB;
;     const unsigned ldsw = (unsigned)wid * 1024u;
;     const int aoff = lds_byte(wr * 64 + fr, fq * 8), boff = lds_byte(wc * 32 + fr, fq * 8);
;     ...
;         PG8_STAGE(PG8_SB(0, 0), cB, voffB); PG8_STAGE(PG8_SB(0, 1), cB + hstepB, voffB); PG8_STAGE(PG8_SA(0, 0), cA, voffA); PG8_STAGE(PG8_SA(0, 1), cA + hstepA, voffA);
;         if (wr == 1) PG8_BAR;
;         PG8_WAIT_V(2); PG8_BAR;
;         PG8_STAGE(PG8_SB(1, 0), cB + kstep, voffB); PG8_STAGE(PG8_SA(1, 0), cA + kstep, voffA); PG8_STAGE(PG8_SB(1, 1), cB + hstepB + kstep, voffB);
;         PG8_WAIT_V(6); PG8_BAR;
.LBB0_1076:
	s_lshl_b32 s10, s10, 5
	s_and_b32 s20, s10, 0x60
	s_mov_b64 s[10:11], 0x80
	s_add_i32 m0, s30, 0x18000
	v_lshl_add_u64 v[6:7], v[6:7], 0, s[10:11]
	s_lshl_b32 s17, s16, 13
	s_lshl_b32 s21, s20, 7
	global_load_lds_dwordx4 v[6:7], off
	v_lshl_add_u64 v[4:5], v[4:5], 0, s[10:11]
	s_add_i32 m0, s30, 0x1a000
	s_add_i32 s47, s30, 0x8000
	s_waitcnt lgkmcnt(0)
	s_add_i32 s54, s30, 0xa000
	global_load_lds_dwordx4 v[4:5], off
	v_lshl_add_u64 v[0:1], v[0:1], 0, s[10:11]
	s_mov_b32 m0, s47
	s_add_u32 s18, s50, 0x80080
	global_load_lds_dwordx4 v[0:1], off
	v_lshl_add_u64 v[0:1], v[2:3], 0, s[10:11]
	s_mov_b32 m0, s54
	s_addc_u32 s19, s51, 0
	global_load_lds_dwordx4 v[0:1], off
	s_add_i32 m0, s30, 0x1c000
	v_lshl_add_u64 v[0:1], s[18:19], 0, v[132:133]
	global_load_lds_dwordx4 v[0:1], off
	v_lshl_add_u64 v[0:1], s[18:19], 0, v[128:129]
	s_add_i32 m0, s30, 0x1e000
	s_sext_i32_i16 s61, s4
	global_load_lds_dwordx4 v[0:1], off
	s_waitcnt vmcnt(8)
	s_barrier
	v_and_b32_e32 v0, 15, v162
	v_lshlrev_b32_e32 v1, 1, v11
	v_lshlrev_b32_e32 v2, 2, v162
	v_lshlrev_b32_e32 v3, 6, v162
	s_movk_i32 s4, 0x3c0
	v_lshl_or_b32 v144, s16, 6, v0
	v_lshl_or_b32 v0, v0, 6, v1
	v_and_b32_e32 v2, 32, v2
	v_and_or_b32 v1, v3, s4, v1
	v_bitop3_b32 v145, s21, v1, v2 bitop3:0xf6
	v_lshlrev_b32_e32 v1, 9, v162
	v_bitop3_b32 v0, v0, s17, v2 bitop3:0xde
	v_and_b32_e32 v1, 0x70000, v1
	v_lshlrev_b32_e32 v2, 12, v12
	v_or3_b32 v1, v9, v1, v2
	v_add_u32_e32 v136, v1, v10
	v_lshlrev_b32_e32 v1, 5, v8
	s_waitcnt vmcnt(6)
	s_cmpk_lt_u32 s5, 0x100
	v_and_b32_e32 v1, 0xf0000, v1
	s_cselect_b64 s[16:17], -1, 0
	v_or3_b32 v1, v9, v1, v2
	s_add_i32 s55, 0, 0x10000
	s_add_i32 s56, 0, 0x14000
	v_or_b32_e32 v146, s20, v11
	v_mov_b32_e32 v137, v133
	v_add_u32_e32 v138, v1, v10
	v_mov_b32_e32 v139, v133
	v_mov_b64_e32 v[140:141], 0x1080
	v_mov_b64_e32 v[142:143], 0x107f
	v_add_u32_e32 v147, s55, v145
	v_add_u32_e32 v148, s56, v145
	v_add_u32_e32 v149, 0, v0
	s_mov_b64 s[18:19], 0x200000
	s_mov_b32 s57, 0x200000
	s_mov_b64 s[20:21], 0x240000
	s_mov_b32 s58, 0x240000
	s_mov_b64 s[22:23], 0x280000
	s_mov_b32 s59, 0x280000
	s_mov_b64 s[36:37], 0x2c0000
	s_mov_b32 s60, 0x2c0000
	s_barrier
	s_branch .LBB0_1079

; #define PG8_STAGE(bufoff, gbase, voff) do { _Pragma("unroll") for (int _i = 0; _i < 2; ++_i) \
;         __builtin_amdgcn_global_load_lds((const unsigned*)((const char*)(gbase) + (voff)[_i]), (PG8_LAS unsigned*)(lds + (bufoff) + ldsw + _i * 8192), 16, 0, 0); } while (0)
; #define PG8_WAIT_V(n) asm volatile("s_waitcnt vmcnt(" #n ")" ::: "memory")
; #define PG8_BAR __builtin_amdgcn_s_barrier()
; template <class Epi, class Sched, bool ALIGN_EPI = false, bool SP2 = false>
; __device__ __forceinline__ void gemm_phase(PG8_LAS unsigned char* lds, const Gemm g, const Sched& S, const Epi& E) {
;     const int tid = threadIdx.x, wid = __builtin_amdgcn_readfirstlane(tid >> 6), lane = tid & 63, wr = wid >> 2, wc = wid & 3, fr = lane & 15, fq = lane >> 4;
;     const int K = g.K, nt = K / BK;
;     unsigned voffA[2], voffB[2];
; #pragma unroll
;     for (int i = 0; i < 2; ++i) { int R, C; stage_rc(tid * 16 + i * 8192, R, C); const int Rb = Epi::PERM ? ((R & ~31) + perm32(R & 31)) : R;
;         voffA[i] = (unsigned)(R * g.lda + C) * 2u; voffB[i] = (unsigned)(Rb * g.ldb + C) * 2u; }
;     const size_t kstep = (size_t)(BK * 2);
;     const size_t hstepA = (size_t)HALF * g.lda * 2, hstepB = (size_t)HALF * g.ldb * 2;
;     const size_t tstepA = 2 * hstepA, tstepB = 2 * hstepB;
;     const unsigned ldsw = (unsigned)wid * 1024u;
;     const int aoff = lds_byte(wr * 64 + fr, fq * 8), boff = lds_byte(wc * 32 + fr, fq * 8);
;     ...
;         PG8_STAGE(PG8_SB(0, 0), cB, voffB); PG8_STAGE(PG8_SB(0, 1), cB + hstepB, voffB); PG8_STAGE(PG8_SA(0, 0), cA, voffA); PG8_STAGE(PG8_SA(0, 1), cA + hstepA, voffA);
;         if (wr == 1) PG8_BAR;
;         PG8_WAIT_V(2); PG8_BAR;
;         PG8_STAGE(PG8_SB(1, 0), cB + kstep, voffB); PG8_STAGE(PG8_SA(1, 0), cA + kstep, voffA); PG8_STAGE(PG8_SB(1, 1), cB + hstepB + kstep, voffB);
;         PG8_WAIT_V(6); PG8_BAR;
.LBB0_1171:
	s_mov_b64 s[16:17], 0x80
	s_lshl_b32 s4, s4, 5
	s_add_i32 m0, s21, 0x18000
	v_lshl_add_u64 v[6:7], v[6:7], 0, s[16:17]
	s_lshl_b32 s19, s1, 13
	s_and_b32 s38, s4, 0x60
	global_load_lds_dwordx4 v[6:7], off
	v_lshl_add_u64 v[4:5], v[4:5], 0, s[16:17]
	s_add_i32 m0, s21, 0x1a000
	s_add_i32 s35, s21, 0x8000
	s_waitcnt lgkmcnt(0)
	s_add_i32 s52, s21, 0xa000
	global_load_lds_dwordx4 v[4:5], off
	v_lshl_add_u64 v[0:1], v[0:1], 0, s[16:17]
	s_mov_b32 m0, s35
	s_add_u32 s4, s48, 0x200080
	global_load_lds_dwordx4 v[0:1], off
	v_lshl_add_u64 v[0:1], v[2:3], 0, s[16:17]
	s_mov_b32 m0, s52
	s_addc_u32 s5, s49, 0
	global_load_lds_dwordx4 v[0:1], off
	s_add_i32 m0, s21, 0x1c000
	v_lshl_add_u64 v[0:1], s[4:5], 0, v[130:131]
	global_load_lds_dwordx4 v[0:1], off
	v_lshl_add_u64 v[0:1], s[4:5], 0, v[134:135]
	s_add_i32 m0, s21, 0x1e000
	v_lshlrev_b32_e32 v2, 14, v148
	global_load_lds_dwordx4 v[0:1], off
	s_waitcnt vmcnt(8)
	s_barrier
	v_lshlrev_b32_e32 v1, 2, v149
	v_lshl_or_b32 v0, v149, 6, v152
	v_and_b32_e32 v1, 32, v1
	v_bitop3_b32 v0, v0, s19, v1 bitop3:0xde
	v_lshlrev_b32_e32 v1, 11, v162
	v_and_b32_e32 v1, 0x1c0000, v1
	v_or3_b32 v1, v146, v1, v2
	v_add_u32_e32 v136, v1, v147
	v_lshlrev_b32_e32 v1, 7, v151
	s_waitcnt vmcnt(6)
	s_cmpk_lt_u32 s0, 0x100
	v_and_b32_e32 v1, 0x3c0000, v1
	v_lshl_or_b32 v145, s38, 7, v153
	s_cselect_b64 s[36:37], -1, 0
	v_or3_b32 v1, v146, v1, v2
	s_add_i32 s53, 0, 0x10000
	s_add_i32 s54, 0, 0x14000
	v_lshl_or_b32 v144, s1, 6, v149
	v_or_b32_e32 v149, s38, v150
	v_mov_b32_e32 v137, v131
	v_add_u32_e32 v138, v1, v147
	v_mov_b32_e32 v139, v131
	v_mov_b64_e32 v[140:141], 0x100
	v_mov_b64_e32 v[142:143], 0xff
	v_add_u32_e32 v146, s53, v145
	v_add_u32_e32 v147, s54, v145
	v_add_u32_e32 v148, 0, v0
	s_add_i32 s55, s21, 0xc000
	s_add_i32 s56, s21, 0xe000
	s_barrier
	s_branch .LBB0_1174

; #define PG8_STAGE(bufoff, gbase, voff) do { _Pragma("unroll") for (int _i = 0; _i < 2; ++_i) \
;         __builtin_amdgcn_global_load_lds((const unsigned*)((const char*)(gbase) + (voff)[_i]), (PG8_LAS unsigned*)(lds + (bufoff) + ldsw + _i * 8192), 16, 0, 0); } while (0)
; #define PG8_WAIT_V(n) asm volatile("s_waitcnt vmcnt(" #n ")" ::: "memory")
; #define PG8_BAR __builtin_amdgcn_s_barrier()
; template <class Epi, class Sched, bool ALIGN_EPI = false, bool SP2 = false>
; __device__ __forceinline__ void gemm_phase(PG8_LAS unsigned char* lds, const Gemm g, const Sched& S, const Epi& E) {
;     const int tid = threadIdx.x, wid = __builtin_amdgcn_readfirstlane(tid >> 6), lane = tid & 63, wr = wid >> 2, wc = wid & 3, fr = lane & 15, fq = lane >> 4;
;     const int K = g.K, nt = K / BK;
;     unsigned voffA[2], voffB[2];
; #pragma unroll
;     for (int i = 0; i < 2; ++i) { int R, C; stage_rc(tid * 16 + i * 8192, R, C); const int Rb = Epi::PERM ? ((R & ~31) + perm32(R & 31)) : R;
;         voffA[i] = (unsigned)(R * g.lda + C) * 2u; voffB[i] = (unsigned)(Rb * g.ldb + C) * 2u; }
;     const size_t kstep = (size_t)(BK * 2);
;     const size_t hstepA = (size_t)HALF * g.lda * 2, hstepB = (size_t)HALF * g.ldb * 2;
;     const size_t tstepA = 2 * hstepA, tstepB = 2 * hstepB;
;     const unsigned ldsw = (unsigned)wid * 1024u;
;     const int aoff = lds_byte(wr * 64 + fr, fq * 8), boff = lds_byte(wc * 32 + fr, fq * 8);
;     ...
;         PG8_STAGE(PG8_SB(0, 0), cB, voffB); PG8_STAGE(PG8_SB(0, 1), cB + hstepB, voffB); PG8_STAGE(PG8_SA(0, 0), cA, voffA); PG8_STAGE(PG8_SA(0, 1), cA + hstepA, voffA);
;         if (wr == 1) PG8_BAR;
;         PG8_WAIT_V(2); PG8_BAR;
;         PG8_STAGE(PG8_SB(1, 0), cB + kstep, voffB); PG8_STAGE(PG8_SA(1, 0), cA + kstep, voffA); PG8_STAGE(PG8_SB(1, 1), cB + hstepB + kstep, voffB);
;         PG8_WAIT_V(6); PG8_BAR;
.LBB0_1327:
	s_lshl_b32 s10, s10, 5
	s_and_b32 s18, s10, 0x60
	s_mov_b64 s[10:11], 0x80
	s_add_i32 m0, s30, 0x18000
	v_lshl_add_u64 v[6:7], v[6:7], 0, s[10:11]
	s_lshl_b32 s15, s14, 13
	s_lshl_b32 s19, s18, 7
	global_load_lds_dwordx4 v[6:7], off
	v_lshl_add_u64 v[2:3], v[2:3], 0, s[10:11]
	s_add_i32 m0, s30, 0x1a000
	s_add_i32 s43, s30, 0x8000
	s_add_i32 s50, s30, 0xa000
	global_load_lds_dwordx4 v[2:3], off
	v_lshl_add_u64 v[0:1], v[0:1], 0, s[10:11]
	s_mov_b32 m0, s43
	s_add_u32 s16, s46, 0x80080
	global_load_lds_dwordx4 v[0:1], off
	v_lshl_add_u64 v[0:1], v[4:5], 0, s[10:11]
	s_mov_b32 m0, s50
	s_addc_u32 s17, s47, 0
	global_load_lds_dwordx4 v[0:1], off
	s_add_i32 m0, s30, 0x1c000
	v_lshl_add_u64 v[0:1], s[16:17], 0, v[132:133]
	global_load_lds_dwordx4 v[0:1], off
	v_lshl_add_u64 v[0:1], s[16:17], 0, v[128:129]
	s_add_i32 m0, s30, 0x1e000
	s_waitcnt lgkmcnt(0)
	s_sext_i32_i8 s57, s4
	global_load_lds_dwordx4 v[0:1], off
	s_waitcnt vmcnt(8)
	s_barrier
	v_and_b32_e32 v0, 15, v162
	v_lshlrev_b32_e32 v1, 1, v11
	v_lshlrev_b32_e32 v2, 2, v162
	v_lshlrev_b32_e32 v3, 6, v162
	s_movk_i32 s4, 0x3c0
	v_lshl_or_b32 v150, s14, 6, v0
	v_lshl_or_b32 v0, v0, 6, v1
	v_and_b32_e32 v2, 32, v2
	v_and_or_b32 v1, v3, s4, v1
	v_bitop3_b32 v151, s19, v1, v2 bitop3:0xf6
	v_lshlrev_b32_e32 v1, 9, v162
	v_bitop3_b32 v0, v0, s15, v2 bitop3:0xde
	v_and_b32_e32 v1, 0x70000, v1
	v_lshlrev_b32_e32 v2, 12, v12
	v_or3_b32 v1, v9, v1, v2
	v_add_u32_e32 v136, v1, v10
	v_lshlrev_b32_e32 v1, 5, v8
	s_waitcnt vmcnt(6)
	s_cmpk_lt_u32 s5, 0x100
	v_and_b32_e32 v1, 0xf0000, v1
	s_cselect_b64 s[14:15], -1, 0
	v_or3_b32 v1, v9, v1, v2
	s_add_i32 s51, 0, 0x10000
	s_add_i32 s52, 0, 0x14000
	v_or_b32_e32 v152, s18, v11
	v_mov_b32_e32 v137, v133
	v_add_u32_e32 v138, v1, v10
	v_mov_b32_e32 v139, v133
	v_mov_b64_e32 v[140:141], 0x420
	v_mov_b64_e32 v[142:143], 0x41f
	v_add_u32_e32 v153, s51, v151
	v_add_u32_e32 v154, s52, v151
	v_add_u32_e32 v155, 0, v0
	s_mov_b32 s53, 0x80000
	s_mov_b64 s[16:17], 0x90000
	s_mov_b32 s54, 0x90000
	s_mov_b64 s[18:19], 0xa0000
	s_mov_b32 s55, 0xa0000
	s_mov_b64 s[20:21], 0xb0000
	s_mov_b32 s56, 0xb0000
	s_barrier
	s_branch .LBB0_1330
